# attention units rescheduled across CUs: D-mixer CUs run latD+ctxD+ctxA, others latC+latB+latA+ctxB+ctxC (balances per-CU attention time)
# baseline (speedup 1.0000x reference)
.LBB0_63:
	v_div_scale_f32 v0, s[8:9], v3, v3, 1.0
	v_rcp_f32_e32 v38, v0
	v_mov_b32_e32 v149, v1
	v_lshl_add_u64 v[36:37], v[148:149], 1, s[84:85]
	s_add_i32 s96, s96, 1
	v_fma_f32 v39, -v0, v38, 1.0
	v_fmac_f32_e32 v38, v39, v38
	v_div_scale_f32 v39, vcc, 1.0, v3, 1.0
	v_mul_f32_e32 v44, v39, v38
	v_fma_f32 v45, -v0, v44, v39
	v_fmac_f32_e32 v44, v45, v38
	v_fma_f32 v0, -v0, v44, v39
	v_div_fmas_f32 v0, v0, v38, v44
	v_div_fixup_f32 v38, v0, v3, 1.0
	v_lshlrev_b32_e32 v0, 12, v167
	v_pk_mul_f32 v[46:47], v[64:65], v[38:39] op_sel_hi:[1,0]
	v_lshl_add_u64 v[36:37], v[36:37], 0, v[0:1]
	v_pk_mul_f32 v[44:45], v[66:67], v[38:39] op_sel_hi:[1,0]
	v_cvt_pk_bf16_f32 v46, v46, v47
	v_pk_mul_f32 v[42:43], v[42:43], v[38:39] op_sel_hi:[1,0]
	v_cvt_pk_bf16_f32 v47, v44, v45
	global_store_dwordx2 v[36:37], v[46:47], off
	v_pk_mul_f32 v[46:47], v[60:61], v[38:39] op_sel_hi:[1,0]
	v_pk_mul_f32 v[44:45], v[62:63], v[38:39] op_sel_hi:[1,0]
	v_cvt_pk_bf16_f32 v46, v46, v47
	v_pk_mul_f32 v[40:41], v[40:41], v[38:39] op_sel_hi:[1,0]
	v_cvt_pk_bf16_f32 v47, v44, v45
	global_store_dwordx2 v[36:37], v[46:47], off offset:32
	v_pk_mul_f32 v[46:47], v[56:57], v[38:39] op_sel_hi:[1,0]
	v_pk_mul_f32 v[44:45], v[58:59], v[38:39] op_sel_hi:[1,0]
	v_cvt_pk_bf16_f32 v46, v46, v47
	v_div_scale_f32 v0, s[8:9], v2, v2, 1.0
	v_cvt_pk_bf16_f32 v47, v44, v45
	global_store_dwordx2 v[36:37], v[46:47], off offset:64
	v_pk_mul_f32 v[46:47], v[52:53], v[38:39] op_sel_hi:[1,0]
	v_pk_mul_f32 v[44:45], v[54:55], v[38:39] op_sel_hi:[1,0]
	v_cvt_pk_bf16_f32 v46, v46, v47
	v_rcp_f32_e32 v3, v0
	v_cvt_pk_bf16_f32 v47, v44, v45
	global_store_dwordx2 v[36:37], v[46:47], off offset:96
	v_cvt_pk_bf16_f32 v40, v40, v41
	v_cvt_pk_bf16_f32 v41, v42, v43
	v_pk_mul_f32 v[42:43], v[68:69], v[38:39] op_sel_hi:[1,0]
	global_store_dwordx2 v[36:37], v[40:41], off offset:128
	v_pk_mul_f32 v[40:41], v[70:71], v[38:39] op_sel_hi:[1,0]
	v_cvt_pk_bf16_f32 v42, v42, v43
	s_mov_b32 s8, 0x10000
	v_cvt_pk_bf16_f32 v43, v40, v41
	global_store_dwordx2 v[36:37], v[42:43], off offset:160
	v_pk_mul_f32 v[40:41], v[74:75], v[38:39] op_sel_hi:[1,0]
	v_pk_mul_f32 v[42:43], v[72:73], v[38:39] op_sel_hi:[1,0]
	s_mov_b64 s[28:29], s[6:7]
	v_cvt_pk_bf16_f32 v42, v42, v43
	v_cvt_pk_bf16_f32 v43, v40, v41
	v_pk_mul_f32 v[40:41], v[78:79], v[38:39] op_sel_hi:[1,0]
	v_pk_mul_f32 v[38:39], v[76:77], v[38:39] op_sel_hi:[1,0]
	global_store_dwordx2 v[36:37], v[42:43], off offset:192
	v_cvt_pk_bf16_f32 v38, v38, v39
	v_cvt_pk_bf16_f32 v39, v40, v41
	global_store_dwordx2 v[36:37], v[38:39], off offset:224
	v_fma_f32 v38, -v0, v3, 1.0
	v_fmac_f32_e32 v3, v38, v3
	v_div_scale_f32 v38, vcc, 1.0, v2, 1.0
	v_mul_f32_e32 v39, v38, v3
	v_fma_f32 v40, -v0, v39, v38
	v_fmac_f32_e32 v39, v40, v3
	v_fma_f32 v0, -v0, v39, v38
	v_div_fmas_f32 v0, v0, v3, v39
	v_div_fixup_f32 v0, v0, v2, 1.0
	v_pk_mul_f32 v[2:3], v[26:27], v[0:1] op_sel_hi:[1,0]
	v_pk_mul_f32 v[24:25], v[24:25], v[0:1] op_sel_hi:[1,0]
	v_pk_mul_f32 v[26:27], v[28:29], v[0:1] op_sel_hi:[1,0]
	v_cvt_pk_bf16_f32 v24, v24, v25
	v_cvt_pk_bf16_f32 v25, v2, v3
	v_add_co_u32_e32 v2, vcc, s8, v36
	s_mul_i32 s8, s96, s50
	s_nop 0
	v_addc_co_u32_e32 v3, vcc, 0, v37, vcc
	global_store_dwordx2 v[2:3], v[24:25], off
	v_pk_mul_f32 v[24:25], v[30:31], v[0:1] op_sel_hi:[1,0]
	v_cvt_pk_bf16_f32 v26, v26, v27
	s_add_i32 s8, s8, s2
	v_cvt_pk_bf16_f32 v27, v24, v25
	global_store_dwordx2 v[2:3], v[26:27], off offset:32
	v_pk_mul_f32 v[26:27], v[32:33], v[0:1] op_sel_hi:[1,0]
	v_pk_mul_f32 v[20:21], v[20:21], v[0:1] op_sel_hi:[1,0]
	v_pk_mul_f32 v[16:17], v[16:17], v[0:1] op_sel_hi:[1,0]
	v_pk_mul_f32 v[12:13], v[12:13], v[0:1] op_sel_hi:[1,0]
	v_pk_mul_f32 v[8:9], v[8:9], v[0:1] op_sel_hi:[1,0]
	v_pk_mul_f32 v[4:5], v[4:5], v[0:1] op_sel_hi:[1,0]
	s_cmpk_lg_i32 s50, 0x100
	s_cbranch_scc1 .Lexit_orig
	s_bfe_u32 s8, s2, 0x20005
	s_lshr_b32 s9, s8, 1
	s_xor_b32 s8, s8, s9
	s_and_b32 s8, s8, 1
	s_lshl_b32 s8, s8, 1
	s_add_i32 s8, s8, 3
	s_cmp_ge_u32 s96, s8
	s_branch .Lexit_done
.Lexit_orig:
	s_cmpk_gt_i32 s8, 0x3ff
.Lexit_done:
	v_pk_mul_f32 v[24:25], v[34:35], v[0:1] op_sel_hi:[1,0]
	v_cvt_pk_bf16_f32 v26, v26, v27
	v_pk_mul_f32 v[22:23], v[22:23], v[0:1] op_sel_hi:[1,0]
	v_cvt_pk_bf16_f32 v27, v24, v25
	global_store_dwordx2 v[2:3], v[26:27], off offset:64
	v_cvt_pk_bf16_f32 v20, v20, v21
	v_cvt_pk_bf16_f32 v21, v22, v23
	global_store_dwordx2 v[2:3], v[20:21], off offset:96
	v_pk_mul_f32 v[18:19], v[18:19], v[0:1] op_sel_hi:[1,0]
	v_cvt_pk_bf16_f32 v16, v16, v17
	v_pk_mul_f32 v[14:15], v[14:15], v[0:1] op_sel_hi:[1,0]
	v_cvt_pk_bf16_f32 v17, v18, v19
	global_store_dwordx2 v[2:3], v[16:17], off offset:128
	v_cvt_pk_bf16_f32 v12, v12, v13
	v_cvt_pk_bf16_f32 v13, v14, v15
	global_store_dwordx2 v[2:3], v[12:13], off offset:160
	v_pk_mul_f32 v[10:11], v[10:11], v[0:1] op_sel_hi:[1,0]
	v_cvt_pk_bf16_f32 v8, v8, v9
	v_pk_mul_f32 v[6:7], v[6:7], v[0:1] op_sel_hi:[1,0]
	v_cvt_pk_bf16_f32 v9, v10, v11
	global_store_dwordx2 v[2:3], v[8:9], off offset:192
	v_cvt_pk_bf16_f32 v4, v4, v5
	v_cvt_pk_bf16_f32 v5, v6, v7
	global_store_dwordx2 v[2:3], v[4:5], off offset:224
	s_cbranch_scc1 .LBB0_161
.LBB0_64:
	s_cmp_lt_u32 s96, 2
	v_readlane_b32 s10, v253, 6
	s_cselect_b64 s[8:9], -1, 0
	v_readlane_b32 s11, v253, 7
	s_and_b64 s[8:9], s[10:11], s[8:9]
	s_sub_i32 s10, 1, s96
	s_and_b64 s[8:9], s[8:9], exec
	s_cselect_b32 s8, s10, s96
	s_mul_i32 s8, s8, s50
	s_add_i32 s8, s8, s2
	s_cmpk_lg_i32 s50, 0x100
	s_cbranch_scc1 .Lmap_done
	s_bfe_u32 s9, s2, 0x20005
	s_lshr_b32 s10, s9, 1
	s_xor_b32 s9, s9, s10
	s_and_b32 s9, s9, 1
	s_and_b32 s11, s2, 31
	s_lshl_b32 s10, s10, 5
	s_or_b32 s11, s11, s10
	s_lshr_b32 s10, s2, 7
	s_lshl_b32 s10, s10, 6
	s_or_b32 s11, s11, s10
	s_cmp_eq_u32 s9, 0
	s_mov_b32 s10, 0x65012
	s_cselect_b32 s10, 0x473, s10
	s_lshl_b32 s9, s96, 2
	s_lshr_b32 s10, s10, s9
	s_and_b32 s10, s10, 15
	s_and_b32 s9, s10, 3
	s_bitcmp1_b32 s10, 2
	s_cbranch_scc1 .Lmap_ctx
	s_lshr_b32 s10, s11, 5
	s_and_b32 s11, s11, 31
	s_cmp_lt_u32 s10, 2
	s_cbranch_scc1 .Lmap_latlo
	s_sub_i32 s9, 3, s9
.Lmap_latlo:
	s_lshl_b32 s10, s10, 7
	s_lshl_b32 s9, s9, 5
	s_or_b32 s8, s10, s9
	s_or_b32 s8, s8, s11
	s_branch .Lmap_done
.Lmap_ctx:
	s_lshl_b32 s9, s9, 7
	s_add_i32 s8, s9, s11
	s_addk_i32 s8, 0x200
.Lmap_done:
	s_cmpk_lt_i32 s8, 0x200
	s_mov_b64 s[6:7], -1
	v_mov_b32_e32 v145, v164
	s_cselect_b64 s[40:41], -1, 0
	s_cmpk_gt_i32 s8, 0x1ff
	s_cbranch_scc0 .LBB0_66
	s_add_i32 s6, s8, 0xfffffe00
	s_lshr_b32 s97, s6, 5
	s_lshl_b32 s6, s8, 8
	s_and_b32 s19, s6, 0x1f00
	s_mov_b64 s[6:7], 0
